# gemm_in epilogue with 16-byte stores from a scalar tile base; static wave priority 1 for the blocks with index bit 8 set
# speedup vs baseline: 1.0360x; 1.0029x over previous
; #define LAS __attribute__((address_space(3)))
; __device__ __forceinline__ unsigned xb_ld(unsigned* p)              { return __hip_atomic_load(p, __ATOMIC_RELAXED, __HIP_MEMORY_SCOPE_AGENT); }
; __device__ __forceinline__ unsigned xb_add(unsigned* p, unsigned v) { return __hip_atomic_fetch_add(p, v, __ATOMIC_RELAXED, __HIP_MEMORY_SCOPE_AGENT); }
; __device__ __forceinline__ unsigned xb_xcc_id() { return (unsigned)__builtin_amdgcn_s_getreg((3 << 11) | 20) & 0xFu; }
; __device__ __forceinline__ XcdBarrier xcd_barrier_post(unsigned* bar, volatile LAS unsigned* st) {
;   XcdBarrier b; b.bar = bar; b.x = xb_xcc_id(); b.st = st;
;   if (threadIdx.x == 0) (void)xb_add(&bar[XB_XCNT(b.x)], 1u);
;   return b;
; }
; __device__ __forceinline__ void xcd_barrier_complete(unsigned* bar, unsigned x, unsigned& nloc, unsigned& nx) {
;   const unsigned G = gridDim.x * gridDim.y * gridDim.z;
;   unsigned sum, cnt, mine, sp = 0u;
;   for (;;) {
;     sum = 0u; cnt = 0u; mine = 0u;
; #pragma unroll
;     for (unsigned j = 0; j < 16; ++j) { const unsigned c = xb_ld(&bar[XB_XCNT(j)]); sum += c; cnt += (c > 0u) ? 1u : 0u; mine = (j == x) ? c : mine; }
; __global__ void __launch_bounds__(256, 2) mega(Params p) {
;   extern __shared__ __attribute__((aligned(16))) unsigned char smem[];
;   cg::grid_group grid = cg::this_grid();
;   const bool multi = (p.phase_hi - p.phase_lo) > 1;
;   XcdBarrier xb; xb.bar = p.BAR; xb.x = 0; xb.st = (volatile LAS unsigned*)(smem + 73736);
;   if (multi) {
;     if (threadIdx.x == 0) { xb.st[0] = 0u; xb.st[1] = 0u; }
;     __syncthreads();
;     xb = xcd_barrier_post(p.BAR, xb.st);
;   }
.LBB0_7:
	v_writelane_b32 v250, s36, 5
	s_load_dwordx16 s[76:91], s[0:1], 0xc0
	s_cmp_le_i32 s11, s10
	v_writelane_b32 v250, s37, 6
	v_writelane_b32 v250, s38, 7
	v_writelane_b32 v250, s39, 8
	v_writelane_b32 v250, s40, 9
	v_writelane_b32 v250, s41, 10
	v_writelane_b32 v250, s42, 11
	v_writelane_b32 v250, s43, 12
	v_writelane_b32 v250, s44, 13
	v_writelane_b32 v250, s45, 14
	v_writelane_b32 v250, s46, 15
	v_writelane_b32 v250, s47, 16
	v_writelane_b32 v250, s48, 17
	v_writelane_b32 v250, s49, 18
	v_writelane_b32 v250, s50, 19
	v_writelane_b32 v250, s51, 20
	s_load_dwordx16 s[36:51], s[0:1], 0x0
	s_waitcnt lgkmcnt(0)
	v_writelane_b32 v250, s36, 21
	s_nop 1
	v_writelane_b32 v250, s37, 22
	v_writelane_b32 v250, s38, 23
	v_writelane_b32 v250, s39, 24
	v_writelane_b32 v250, s40, 25
	v_writelane_b32 v250, s41, 26
	v_writelane_b32 v250, s42, 27
	v_writelane_b32 v250, s43, 28
	v_writelane_b32 v250, s44, 29
	v_writelane_b32 v250, s45, 30
	v_writelane_b32 v250, s46, 31
	v_writelane_b32 v250, s47, 32
	v_writelane_b32 v250, s48, 33
	v_writelane_b32 v250, s49, 34
	v_writelane_b32 v250, s50, 35
	v_writelane_b32 v250, s51, 36
	s_load_dwordx16 s[36:51], s[0:1], 0x40
	s_waitcnt lgkmcnt(0)
	v_writelane_b32 v250, s36, 37
	s_nop 1
	v_writelane_b32 v250, s37, 38
	v_writelane_b32 v250, s38, 39
	v_writelane_b32 v250, s39, 40
	v_writelane_b32 v250, s40, 41
	v_writelane_b32 v250, s41, 42
	v_writelane_b32 v250, s42, 43
	v_writelane_b32 v250, s43, 44
	v_writelane_b32 v250, s44, 45
	v_writelane_b32 v250, s45, 46
	v_writelane_b32 v250, s46, 47
	v_writelane_b32 v250, s47, 48
	v_writelane_b32 v250, s48, 49
	v_writelane_b32 v250, s49, 50
	v_writelane_b32 v250, s50, 51
	v_writelane_b32 v250, s51, 52
	s_load_dwordx16 s[36:51], s[0:1], 0x80
	s_waitcnt lgkmcnt(0)
	v_writelane_b32 v250, s36, 53
	s_nop 1
	v_writelane_b32 v250, s37, 54
	v_writelane_b32 v250, s38, 55
	v_writelane_b32 v250, s39, 56
	v_writelane_b32 v250, s40, 57
	v_writelane_b32 v250, s41, 58
	v_writelane_b32 v250, s42, 59
	v_writelane_b32 v249, s47, 0
	v_writelane_b32 v250, s43, 60
	v_writelane_b32 v249, s48, 1
	v_writelane_b32 v250, s44, 61
	v_writelane_b32 v249, s49, 2
	v_writelane_b32 v250, s45, 62
	v_writelane_b32 v249, s50, 3
	v_writelane_b32 v250, s46, 63
	v_writelane_b32 v249, s51, 4
	s_cbranch_scc1 .LBB0_477
	v_readlane_b32 s2, v250, 1
	s_mov_b64 s[4:5], s[8:9]
	v_readlane_b32 s3, v250, 2
	s_mov_b64 s[6:7], s[10:11]
	s_mul_i32 s0, s3, s2
	s_add_i32 s1, s6, 1
	v_readlane_b32 s36, v250, 5
	v_writelane_b32 v249, s1, 5
	s_mul_i32 s0, s0, s21
	v_readlane_b32 s50, v250, 19
	v_writelane_b32 v249, s0, 6
	v_readlane_b32 s51, v250, 20
	s_add_u32 s0, s50, 0x200
	s_addc_u32 s1, s51, 0
	v_writelane_b32 v249, s0, 7
	v_readlane_b32 s37, v250, 6
	s_mov_b32 s37, 0
	v_writelane_b32 v249, s1, 8
	s_add_u32 s0, s50, 0x1000
	s_addc_u32 s1, s51, 0
	v_writelane_b32 v249, s0, 9
	v_and_b32_e32 v147, 0x3ff, v0
	v_and_b32_e32 v0, 0x3fffffff, v0
	v_writelane_b32 v249, s1, 10
	s_add_u32 s0, s50, 0x1100
	s_addc_u32 s1, s51, 0
	v_writelane_b32 v249, s0, 11
	v_mov_b32_e32 v145, 0
	v_mbcnt_lo_u32_b32 v1, -1, 0
	v_writelane_b32 v249, s1, 12
	s_add_u32 s0, s50, 0x1200
	s_addc_u32 s1, s51, 0
	v_writelane_b32 v249, s0, 13
	v_mbcnt_hi_u32_b32 v209, -1, v1
	v_and_b32_e32 v1, 64, v209
	v_writelane_b32 v249, s1, 14
	s_add_u32 s0, s50, 0x1300
	s_addc_u32 s1, s51, 0
	v_writelane_b32 v249, s0, 15
	s_cmp_eq_u32 s20, 15
	v_mov_b32_e32 v206, 1
	v_writelane_b32 v249, s1, 16
	s_cselect_b64 s[0:1], -1, 0
	v_writelane_b32 v249, s0, 17
	s_cmp_eq_u32 s20, 14
	v_mov_b32_e32 v146, 0x358637bd
	v_writelane_b32 v249, s1, 18
	s_cselect_b64 s[0:1], -1, 0
	v_writelane_b32 v249, s0, 19
	s_cmp_eq_u32 s20, 13
	v_mov_b32_e32 v207, 0x260
	v_writelane_b32 v249, s1, 20
	s_cselect_b64 s[0:1], -1, 0
	v_writelane_b32 v249, s0, 21
	s_cmp_eq_u32 s20, 12
	v_mov_b32_e32 v208, 0x3ecc95a3
	v_writelane_b32 v249, s1, 22
	s_cselect_b64 s[0:1], -1, 0
	v_writelane_b32 v249, s0, 23
	s_cmp_eq_u32 s20, 11
	v_add_u32_e32 v210, 64, v1
	v_writelane_b32 v249, s1, 24
	s_cselect_b64 s[0:1], -1, 0
	v_writelane_b32 v249, s0, 25
	s_cmp_eq_u32 s20, 10
	v_xor_b32_e32 v211, 32, v209
	v_writelane_b32 v249, s1, 26
	s_cselect_b64 s[0:1], -1, 0
	v_writelane_b32 v249, s0, 27
	s_cmp_eq_u32 s20, 9
	v_xor_b32_e32 v212, 16, v209
	v_writelane_b32 v249, s1, 28
	s_cselect_b64 s[0:1], -1, 0
	v_writelane_b32 v249, s0, 29
	s_cmp_eq_u32 s20, 8
	v_xor_b32_e32 v213, 8, v209
	v_writelane_b32 v249, s1, 30
	s_cselect_b64 s[0:1], -1, 0
	v_writelane_b32 v249, s0, 31
	s_cmp_eq_u32 s20, 7
	v_mov_b32_e32 v214, 0x3eb60549
	v_writelane_b32 v249, s1, 32
	s_cselect_b64 s[0:1], -1, 0
	v_writelane_b32 v249, s0, 33
	s_cmp_eq_u32 s20, 6
	v_mov_b32_e32 v215, 0x3e4ccccd
	v_writelane_b32 v249, s1, 34
	s_cselect_b64 s[0:1], -1, 0
	v_writelane_b32 v249, s0, 35
	s_cmp_eq_u32 s20, 5
	v_mov_b32_e32 v216, 0x8000
	v_writelane_b32 v249, s1, 36
	s_cselect_b64 s[0:1], -1, 0
	v_writelane_b32 v249, s0, 37
	s_cmp_eq_u32 s20, 4
; #define LAS __attribute__((address_space(3)))
; __global__ void __launch_bounds__(256, 2) mega(Params p) {
;   extern __shared__ __attribute__((aligned(16))) unsigned char smem[];
;   cg::grid_group grid = cg::this_grid();
;   const bool multi = (p.phase_hi - p.phase_lo) > 1;
;   XcdBarrier xb; xb.bar = p.BAR; xb.x = 0; xb.st = (volatile LAS unsigned*)(smem + 73736);
;   if (multi) {
;     if (threadIdx.x == 0) { xb.st[0] = 0u; xb.st[1] = 0u; }
;     __syncthreads();
;     xb = xcd_barrier_post(p.BAR, xb.st);
;   }
	v_bfrev_b32_e32 v217, 1
	v_writelane_b32 v249, s1, 38
	s_cselect_b64 s[0:1], -1, 0
	v_writelane_b32 v249, s0, 39
	s_cmp_eq_u32 s20, 3
	v_mov_b32_e32 v218, 0x1a00
	v_writelane_b32 v249, s1, 40
	s_cselect_b64 s[0:1], -1, 0
	v_writelane_b32 v249, s0, 41
	s_cmp_eq_u32 s20, 2
	v_mov_b32_e32 v219, 0x900
	v_writelane_b32 v249, s1, 42
	s_cselect_b64 s[0:1], -1, 0
	v_writelane_b32 v249, s0, 43
	s_cmp_eq_u32 s20, 1
	v_mov_b32_e32 v220, 0x1200
	v_writelane_b32 v249, s1, 44
	s_cselect_b64 s[0:1], -1, 0
	v_writelane_b32 v249, s0, 45
	s_cmp_eq_u32 s20, 0
	v_mov_b32_e32 v221, 0x41b17218
	v_writelane_b32 v249, s1, 46
	s_cselect_b64 s[0:1], -1, 0
	v_writelane_b32 v249, s0, 47
	v_mov_b32_e32 v222, 0x7ff
	v_mov_b32_e32 v223, 0xfff
	v_writelane_b32 v249, s1, 48
	s_lshl_b32 s0, s20, 8
	s_add_u32 s0, s50, s0
	s_addc_u32 s1, s51, 0
	s_add_u32 s8, s0, 0x1400
	s_addc_u32 s9, s1, 0
	v_writelane_b32 v249, s8, 49
	s_add_u32 s0, s0, 0x2400
	s_addc_u32 s1, s1, 0
	v_writelane_b32 v249, s9, 50
	v_writelane_b32 v249, s0, 51
	v_mov_b32_e32 v224, 0x385f10d2
	v_mov_b32_e32 v225, 0x3ab95d22
	v_writelane_b32 v249, s1, 52
	s_add_u32 s0, s50, 0x3400
	s_addc_u32 s1, s51, 0
	v_writelane_b32 v249, s0, 53
	v_mov_b32_e32 v148, 0x3f317218
	v_mov_b32_e32 v226, 0x7f800000
	v_writelane_b32 v249, s1, 54
	s_add_u32 s0, s50, 0x3500
	s_addc_u32 s1, s51, 0
	v_writelane_b32 v249, s0, 55
	v_mov_b32_e32 v227, 0x7fc00000
	v_mov_b32_e32 v228, 0xff800000
	v_writelane_b32 v249, s1, 56
	s_and_b32 s1, s2, 7
	s_lshl_b32 s0, s2, 2
	s_cmp_lg_u32 s1, 0
	s_cselect_b64 s[8:9], -1, 0
	v_writelane_b32 v249, s8, 57
	s_ashr_i32 s3, s2, 3
	s_ashr_i32 s1, s0, 31
	v_writelane_b32 v249, s9, 58
	s_mul_i32 s8, s2, 0x6800
	s_mul_hi_i32 s9, s0, 0x1a00
	v_writelane_b32 v249, s8, 59
	s_lshl_b32 s24, s2, 3
	s_movk_i32 s26, 0x1a00
	v_writelane_b32 v249, s9, 60
	v_writelane_b32 v249, s3, 61
	s_lshl_b32 s3, s2, 8
	v_writelane_b32 v249, s3, 62
	s_lshl_b32 s3, s2, 6
	s_add_u32 s2, s80, 4
	v_writelane_b32 v249, s3, 63
	s_addc_u32 s3, s81, 0
	v_writelane_b32 v248, s2, 0
	v_readlane_b32 s8, v250, 37
	v_readlane_b32 s14, v250, 43
	v_writelane_b32 v248, s3, 1
	s_lshl_b64 s[2:3], s[0:1], 11
	v_writelane_b32 v248, s2, 2
	s_mov_b32 s1, s37
	v_readlane_b32 s15, v250, 44
	v_writelane_b32 v248, s3, 3
	v_writelane_b32 v248, s0, 4
	v_readlane_b32 s18, v250, 47
	v_readlane_b32 s19, v250, 48
	v_writelane_b32 v248, s1, 5
	s_mov_b32 s0, s14
	v_writelane_b32 v248, s0, 6
	s_mov_b32 s0, s15
	v_writelane_b32 v248, s0, 7
	s_mov_b32 s0, s14
	v_writelane_b32 v248, s0, 8
	s_mov_b32 s0, s15
	v_writelane_b32 v248, s0, 9
	s_mov_b32 s0, s18
	v_writelane_b32 v248, s0, 10
	s_mov_b32 s0, s19
	v_writelane_b32 v248, s0, 11
	s_mov_b32 s0, s18
	v_writelane_b32 v248, s0, 12
	s_mov_b32 s0, s19
	v_writelane_b32 v248, s0, 13
	s_add_i32 s0, 0, 0x12008
	v_writelane_b32 v248, s0, 14
	s_add_i32 s0, 0, 0x1200c
	v_writelane_b32 v248, s0, 15
	s_add_i32 s0, 0, 0x10600
	v_writelane_b32 v248, s0, 16
	s_add_i32 s0, 0, 0x10d00
	v_writelane_b32 v248, s0, 17
	s_add_i32 s0, 0, 0x10c00
	v_writelane_b32 v248, s0, 18
	s_add_i32 s0, 0, 0x10b00
	v_writelane_b32 v248, s0, 19
	s_add_i32 s0, 0, 0x10a00
	v_writelane_b32 v248, s0, 20
	s_add_i32 s0, 0, 0x12000
	v_writelane_b32 v248, s0, 21
	s_add_i32 s0, 0, 0xf400
	v_writelane_b32 v248, s0, 22
	s_add_i32 s0, 0, 0x11800
	v_writelane_b32 v248, s0, 23
	v_cmp_eq_u32_e64 s[0:1], 0, v147
	s_ashr_i32 s25, s24, 31
	s_mov_b32 s8, s6
	v_writelane_b32 v248, s0, 24
	s_mov_b32 s33, 0x800000
	s_movk_i32 s27, 0x900
	v_writelane_b32 v248, s1, 25
	v_cmp_eq_u32_e64 s[0:1], 0, v0
	s_movk_i32 s28, 0x90
	s_movk_i32 s29, 0x7ff
	v_writelane_b32 v248, s0, 26
	s_mov_b32 s3, 0x3f317217
	s_mov_b32 s2, 0x7f800000
	v_writelane_b32 v248, s1, 27
	v_writelane_b32 v248, s24, 28
	s_lshl_b64 s[0:1], s[24:25], 11
	s_mov_b64 s[34:35], 0x20040
	v_writelane_b32 v248, s25, 29
	v_writelane_b32 v248, s0, 30
	s_mov_b64 s[70:71], 0x40040
	s_mov_b32 s96, 0x3f803f80
	v_writelane_b32 v248, s1, 31
	v_writelane_b32 v248, s4, 32
	s_mov_b64 s[0:1], 0x60040
	v_readlane_b32 s38, v250, 7
	v_writelane_b32 v248, s5, 33
	v_writelane_b32 v248, s6, 34
	v_readlane_b32 s39, v250, 8
	v_readlane_b32 s40, v250, 9
	v_readlane_b32 s41, v250, 10
	v_readlane_b32 s42, v250, 11
	v_readlane_b32 s43, v250, 12
	v_readlane_b32 s44, v250, 13
	v_readlane_b32 s45, v250, 14
	v_readlane_b32 s46, v250, 15
	v_readlane_b32 s47, v250, 16
	v_readlane_b32 s48, v250, 17
	v_readlane_b32 s49, v250, 18
	v_readlane_b32 s9, v250, 38
	v_readlane_b32 s10, v250, 39
	v_readlane_b32 s11, v250, 40
	v_readlane_b32 s12, v250, 41
	v_readlane_b32 s13, v250, 42
	v_readlane_b32 s16, v250, 45
	v_readlane_b32 s17, v250, 46
	v_readlane_b32 s20, v250, 49
	v_readlane_b32 s21, v250, 50
	v_readlane_b32 s22, v250, 51
	v_readlane_b32 s23, v250, 52
	v_writelane_b32 v248, s7, 35
	v_readlane_b32 s4, v250, 0
	s_nop 0
	s_bitcmp1_b32 s4, 8
	s_cbranch_scc0 .Lgprio_skip
	s_setprio 1
.Lgprio_skip:
	v_readlane_b32 s4, v248, 32
	s_branch .LBB0_11

; #define ISSUE_TILE(kt_, stg_) do { \
;     unsigned char* sb_ = wbase + (stg_) * STG; const u16* pa_ = ga + (kt_) * 32; const u16* pb_ = gb + (kt_) * 32; \
;     GLDS16(pa_, sb_); GLDS16(pa_ + sa64, sb_ + 4096); \
;     GLDS16(pb_, sb_ + 8192); GLDS16(pb_ + sb64, sb_ + 8192 + 4096); \
;     GLDS16(pb_ + 2 * sb64, sb_ + 8192 + 8192); GLDS16(pb_ + 3 * sb64, sb_ + 8192 + 12288); } while (0)
; __device__ __forceinline__ void gemm_mainloop3(const u16* __restrict__ A, int lda, const u16* __restrict__ B, int ldb,
;                                                int K, f32x4 (&acc)[4][8], unsigned char* smb) {
;     ...
;   for (int kt = 0; kt < nk; ++kt) {
;     const int cur = kt & 1;
;     if (kt + 1 < nk) ISSUE_TILE(kt + 1, cur ^ 1);
;     __builtin_amdgcn_sched_barrier(0);
;     const unsigned char* cA = smb + cur * STG + (wm * 64 + l15) * 64 + csw;
;     const unsigned char* cB = smb + cur * STG + 8192 + (wn * 128 + l15) * 64 + csw;
;     bf16x8 af[4];
; #pragma unroll
;     for (int i = 0; i < 4; ++i) af[i] = *(const bf16x8*)(cA + i * 16 * 64);
; #pragma unroll
;     for (int nh = 0; nh < 2; ++nh) {
;       bf16x8 bfr[4];
; #pragma unroll
;       for (int i = 0; i < 4; ++i) bfr[i] = *(const bf16x8*)(cB + (nh * 4 + i) * 16 * 64);
; #pragma unroll
;       for (int nt = 0; nt < 4; ++nt)
; #pragma unroll
;         for (int mt = 0; mt < 4; ++mt) acc[mt][nh * 4 + nt] = mfma16(bfr[nt], af[mt], acc[mt][nh * 4 + nt]);
;     }
;     __builtin_amdgcn_sched_group_barrier(0x100, 6, 0);
; #pragma unroll
;     for (int i = 0; i < 6; ++i) {
;       __builtin_amdgcn_sched_group_barrier(0x008, 4, 0);
;       __builtin_amdgcn_sched_group_barrier(0x100, 1, 0);
;     }
;     __builtin_amdgcn_sched_group_barrier(0x008, 8, 0);
;     __builtin_amdgcn_sched_barrier(0);
;     asm volatile("s_waitcnt vmcnt(0)" ::: "memory");
;     __syncthreads();
;   }
.LBB0_401:
	v_add3_u32 v144, s45, v135, v133
	ds_read_b128 v[136:139], v144 offset:8192
	ds_read_b128 v[162:165], v144 offset:9216
	v_add3_u32 v149, s45, v134, v133
	ds_read_b128 v[140:143], v149
	ds_read_b128 v[150:153], v149 offset:1024
	ds_read_b128 v[154:157], v149 offset:2048
	ds_read_b128 v[158:161], v149 offset:3072
	s_add_i32 m0, s44, s50
	v_lshl_add_u64 v[172:173], v[128:129], 0, s[42:43]
	v_lshl_add_u64 v[174:175], v[172:173], 0, 64
	global_load_lds_dwordx4 v[174:175], off
	s_waitcnt lgkmcnt(0)
	v_mfma_f32_16x16x32_bf16 v[124:127], v[136:139], v[140:143], v[124:127]
	v_mfma_f32_16x16x32_bf16 v[108:111], v[136:139], v[150:153], v[108:111]
	v_mfma_f32_16x16x32_bf16 v[80:83], v[136:139], v[154:157], v[80:83]
	v_mfma_f32_16x16x32_bf16 v[36:39], v[136:139], v[158:161], v[36:39]
	ds_read_b128 v[136:139], v144 offset:10240
	s_add_i32 m0, m0, 0x1000
	v_lshl_add_u64 v[172:173], v[172:173], 0, s[34:35]
	global_load_lds_dwordx4 v[172:173], off
	v_mfma_f32_16x16x32_bf16 v[120:123], v[162:165], v[140:143], v[120:123]
	v_mfma_f32_16x16x32_bf16 v[100:103], v[162:165], v[150:153], v[100:103]
	v_mfma_f32_16x16x32_bf16 v[68:71], v[162:165], v[154:157], v[68:71]
	v_mfma_f32_16x16x32_bf16 v[24:27], v[162:165], v[158:161], v[24:27]
	ds_read_b128 v[162:165], v144 offset:11264
	s_add_i32 m0, m0, 0x1000
	v_lshl_add_u64 v[174:175], v[130:131], 0, s[48:49]
	global_load_lds_dwordx4 v[174:175], off
	s_waitcnt lgkmcnt(0)
	v_mfma_f32_16x16x32_bf16 v[116:119], v[136:139], v[140:143], v[116:119]
	v_mfma_f32_16x16x32_bf16 v[92:95], v[136:139], v[150:153], v[92:95]
	v_mfma_f32_16x16x32_bf16 v[48:51], v[136:139], v[154:157], v[48:51]
	v_mfma_f32_16x16x32_bf16 v[12:15], v[136:139], v[158:161], v[12:15]
	ds_read_b128 v[136:139], v144 offset:12288
	s_add_i32 m0, m0, 0x1000
	v_lshl_add_u64 v[172:173], v[166:167], 0, s[48:49]
	global_load_lds_dwordx4 v[172:173], off
	v_mfma_f32_16x16x32_bf16 v[112:115], v[162:165], v[140:143], v[112:115]
	v_mfma_f32_16x16x32_bf16 v[84:87], v[162:165], v[150:153], v[84:87]
	v_mfma_f32_16x16x32_bf16 v[40:43], v[162:165], v[154:157], v[40:43]
	v_mfma_f32_16x16x32_bf16 v[4:7], v[162:165], v[158:161], v[4:7]
	ds_read_b128 v[162:165], v144 offset:13312
	s_add_i32 m0, m0, 0x1000
	v_lshl_add_u64 v[174:175], v[168:169], 0, s[48:49]
	global_load_lds_dwordx4 v[174:175], off
	s_waitcnt lgkmcnt(0)
	v_mfma_f32_16x16x32_bf16 v[104:107], v[136:139], v[140:143], v[104:107]
	v_mfma_f32_16x16x32_bf16 v[72:75], v[136:139], v[150:153], v[72:75]
	v_mfma_f32_16x16x32_bf16 v[28:31], v[136:139], v[154:157], v[28:31]
	v_mfma_f32_16x16x32_bf16 v[0:3], v[136:139], v[158:161], v[0:3]
	ds_read_b128 v[136:139], v144 offset:14336
	s_add_i32 m0, m0, 0x1000
	v_lshl_add_u64 v[172:173], v[170:171], 0, s[48:49]
	global_load_lds_dwordx4 v[172:173], off
	v_mfma_f32_16x16x32_bf16 v[96:99], v[162:165], v[140:143], v[96:99]
	v_mfma_f32_16x16x32_bf16 v[64:67], v[162:165], v[150:153], v[64:67]
	v_mfma_f32_16x16x32_bf16 v[16:19], v[162:165], v[154:157], v[16:19]
	v_mfma_f32_16x16x32_bf16 v[8:11], v[162:165], v[158:161], v[8:11]
	ds_read_b128 v[162:165], v144 offset:15360
	s_waitcnt lgkmcnt(0)
	v_mfma_f32_16x16x32_bf16 v[88:91], v[136:139], v[140:143], v[88:91]
	v_mfma_f32_16x16x32_bf16 v[56:59], v[136:139], v[150:153], v[56:59]
	v_mfma_f32_16x16x32_bf16 v[32:35], v[136:139], v[154:157], v[32:35]
	v_mfma_f32_16x16x32_bf16 v[20:23], v[136:139], v[158:161], v[20:23]
	v_mfma_f32_16x16x32_bf16 v[76:79], v[162:165], v[140:143], v[76:79]
	v_mfma_f32_16x16x32_bf16 v[52:55], v[162:165], v[150:153], v[52:55]
	v_mfma_f32_16x16x32_bf16 v[44:47], v[162:165], v[154:157], v[44:47]
	v_mfma_f32_16x16x32_bf16 v[60:63], v[162:165], v[158:161], v[60:63]
	s_add_u32 s42, s42, 64
	s_addc_u32 s43, s43, 0
	s_add_i32 s48, s48, 0x34000
	s_add_i32 s45, s45, 0x6000
	s_cmp_eq_u32 s45, 0x12000
	s_cselect_b32 s45, 0, s45
	s_add_i32 s50, s50, 0x6000
	s_cmp_eq_u32 s50, 0x12000
	s_cselect_b32 s50, 0, s50
	s_cmpk_lg_i32 s42, 0x780
	s_waitcnt vmcnt(6)
	s_barrier
	s_cbranch_scc1 .LBB0_401
	v_add3_u32 v144, 0, v135, v133
	ds_read_b128 v[136:139], v144 offset:8192
	ds_read_b128 v[162:165], v144 offset:9216
	v_add3_u32 v149, 0, v134, v133
	ds_read_b128 v[140:143], v149
	ds_read_b128 v[150:153], v149 offset:1024
	ds_read_b128 v[154:157], v149 offset:2048
	ds_read_b128 v[158:161], v149 offset:3072
	s_waitcnt lgkmcnt(0)
	v_mfma_f32_16x16x32_bf16 v[124:127], v[136:139], v[140:143], v[124:127]
	v_mfma_f32_16x16x32_bf16 v[108:111], v[136:139], v[150:153], v[108:111]
	v_mfma_f32_16x16x32_bf16 v[80:83], v[136:139], v[154:157], v[80:83]
	v_mfma_f32_16x16x32_bf16 v[36:39], v[136:139], v[158:161], v[36:39]
	ds_read_b128 v[136:139], v144 offset:10240
	v_mfma_f32_16x16x32_bf16 v[120:123], v[162:165], v[140:143], v[120:123]
	v_mfma_f32_16x16x32_bf16 v[100:103], v[162:165], v[150:153], v[100:103]
	v_mfma_f32_16x16x32_bf16 v[68:71], v[162:165], v[154:157], v[68:71]
	v_mfma_f32_16x16x32_bf16 v[24:27], v[162:165], v[158:161], v[24:27]
	ds_read_b128 v[162:165], v144 offset:11264
	s_waitcnt lgkmcnt(0)
	v_mfma_f32_16x16x32_bf16 v[116:119], v[136:139], v[140:143], v[116:119]
	v_mfma_f32_16x16x32_bf16 v[92:95], v[136:139], v[150:153], v[92:95]
	v_mfma_f32_16x16x32_bf16 v[48:51], v[136:139], v[154:157], v[48:51]
	v_mfma_f32_16x16x32_bf16 v[12:15], v[136:139], v[158:161], v[12:15]
	ds_read_b128 v[136:139], v144 offset:12288
	v_mfma_f32_16x16x32_bf16 v[112:115], v[162:165], v[140:143], v[112:115]
	v_mfma_f32_16x16x32_bf16 v[84:87], v[162:165], v[150:153], v[84:87]
	v_mfma_f32_16x16x32_bf16 v[40:43], v[162:165], v[154:157], v[40:43]
	v_mfma_f32_16x16x32_bf16 v[4:7], v[162:165], v[158:161], v[4:7]
	ds_read_b128 v[162:165], v144 offset:13312
	s_waitcnt lgkmcnt(0)
	v_mfma_f32_16x16x32_bf16 v[104:107], v[136:139], v[140:143], v[104:107]
	v_mfma_f32_16x16x32_bf16 v[72:75], v[136:139], v[150:153], v[72:75]
	v_mfma_f32_16x16x32_bf16 v[28:31], v[136:139], v[154:157], v[28:31]
	v_mfma_f32_16x16x32_bf16 v[0:3], v[136:139], v[158:161], v[0:3]
	ds_read_b128 v[136:139], v144 offset:14336
	v_mfma_f32_16x16x32_bf16 v[96:99], v[162:165], v[140:143], v[96:99]
	v_mfma_f32_16x16x32_bf16 v[64:67], v[162:165], v[150:153], v[64:67]
	v_mfma_f32_16x16x32_bf16 v[16:19], v[162:165], v[154:157], v[16:19]
	v_mfma_f32_16x16x32_bf16 v[8:11], v[162:165], v[158:161], v[8:11]
	ds_read_b128 v[162:165], v144 offset:15360
	s_waitcnt lgkmcnt(0)
	v_mfma_f32_16x16x32_bf16 v[88:91], v[136:139], v[140:143], v[88:91]
	v_mfma_f32_16x16x32_bf16 v[56:59], v[136:139], v[150:153], v[56:59]
	v_mfma_f32_16x16x32_bf16 v[32:35], v[136:139], v[154:157], v[32:35]
	v_mfma_f32_16x16x32_bf16 v[20:23], v[136:139], v[158:161], v[20:23]
	v_mfma_f32_16x16x32_bf16 v[76:79], v[162:165], v[140:143], v[76:79]
	v_mfma_f32_16x16x32_bf16 v[52:55], v[162:165], v[150:153], v[52:55]
	v_mfma_f32_16x16x32_bf16 v[44:47], v[162:165], v[154:157], v[44:47]
	v_mfma_f32_16x16x32_bf16 v[60:63], v[162:165], v[158:161], v[60:63]
	s_waitcnt vmcnt(0)
	s_barrier
; __device__ __forceinline__ int TIDX() { int t = threadIdx.x; asm volatile("" : "+v"(t)); return t; }
; __device__ __forceinline__ void gemm_mainloop3(const u16* __restrict__ A, int lda, const u16* __restrict__ B, int ldb,
;                                                int K, f32x4 (&acc)[4][8], unsigned char* smb) {
;     ...
;     for (int nh = 0; nh < 2; ++nh) {
;       bf16x8 bfr[4];
; #pragma unroll
;       for (int i = 0; i < 4; ++i) bfr[i] = *(const bf16x8*)(cB + (nh * 4 + i) * 16 * 64);
; #pragma unroll
;       for (int nt = 0; nt < 4; ++nt)
; #pragma unroll
;         for (int mt = 0; mt < 4; ++mt) acc[mt][nh * 4 + nt] = mfma16(bfr[nt], af[mt], acc[mt][nh * 4 + nt]);
; __device__ __forceinline__ void acc2_to_lds(const f32x4 (&acc)[4][8], float* ct, int hf) {
;   const int tid = TIDX(), lane = tid & 63, w = tid >> 6, wm = w >> 1, wn = w & 1, l15 = lane & 15, g = lane >> 4;
; #pragma unroll
;   for (int mt = 0; mt < 4; ++mt)
; #pragma unroll
;     for (int nt = 0; nt < 4; ++nt)
;       *(f32x4*)(ct + (wm * 64 + mt * 16 + l15) * 132 + wn * 64 + nt * 16 + 4 * g) = acc[mt][hf * 4 + nt];
;   __syncthreads();
	v_add3_u32 v144, 0, v135, v133
	ds_read_b128 v[128:131], v144 offset:32768
	ds_read_b128 v[154:157], v144 offset:33792
	v_add3_u32 v149, 0, v134, v133
	ds_read_b128 v[132:135], v149 offset:24576
	ds_read_b128 v[136:139], v149 offset:25600
	ds_read_b128 v[140:143], v149 offset:26624
	ds_read_b128 v[150:153], v149 offset:27648
	s_waitcnt lgkmcnt(3)
	v_mfma_f32_16x16x32_bf16 v[124:127], v[128:131], v[132:135], v[124:127]
	s_waitcnt lgkmcnt(2)
	v_mfma_f32_16x16x32_bf16 v[108:111], v[128:131], v[136:139], v[108:111]
	s_waitcnt lgkmcnt(1)
	v_mfma_f32_16x16x32_bf16 v[80:83], v[128:131], v[140:143], v[80:83]
	s_waitcnt lgkmcnt(0)
	v_mfma_f32_16x16x32_bf16 v[128:131], v[128:131], v[150:153], v[36:39]
	s_nop 2
	ds_read_b128 v[36:39], v144 offset:34816
	v_mfma_f32_16x16x32_bf16 v[120:123], v[154:157], v[132:135], v[120:123]
	v_mfma_f32_16x16x32_bf16 v[100:103], v[154:157], v[136:139], v[100:103]
	v_mfma_f32_16x16x32_bf16 v[158:161], v[154:157], v[140:143], v[68:71]
	v_mfma_f32_16x16x32_bf16 v[154:157], v[154:157], v[150:153], v[24:27]
	s_nop 2
	ds_read_b128 v[24:27], v144 offset:35840
	s_waitcnt lgkmcnt(1)
	v_mfma_f32_16x16x32_bf16 v[116:119], v[36:39], v[132:135], v[116:119]
	v_mfma_f32_16x16x32_bf16 v[92:95], v[36:39], v[136:139], v[92:95]
	v_mfma_f32_16x16x32_bf16 v[162:165], v[36:39], v[140:143], v[48:51]
	v_mfma_f32_16x16x32_bf16 v[166:169], v[36:39], v[150:153], v[12:15]
	ds_read_b128 v[36:39], v144 offset:36864
	s_waitcnt lgkmcnt(1)
	v_mfma_f32_16x16x32_bf16 v[112:115], v[24:27], v[132:135], v[112:115]
	v_mfma_f32_16x16x32_bf16 v[170:173], v[24:27], v[136:139], v[84:87]
	v_mfma_f32_16x16x32_bf16 v[174:177], v[24:27], v[140:143], v[40:43]
	v_mfma_f32_16x16x32_bf16 v[178:181], v[24:27], v[150:153], v[4:7]
	s_nop 1
	ds_read_b128 v[40:43], v144 offset:37888
	s_waitcnt lgkmcnt(1)
	v_mfma_f32_16x16x32_bf16 v[24:27], v[36:39], v[132:135], v[104:107]
	v_mfma_f32_16x16x32_bf16 v[12:15], v[36:39], v[136:139], v[72:75]
	v_mfma_f32_16x16x32_bf16 v[4:7], v[36:39], v[140:143], v[28:31]
	v_mfma_f32_16x16x32_bf16 v[0:3], v[36:39], v[150:153], v[0:3]
	ds_read_b128 v[68:71], v144 offset:38912
	s_waitcnt lgkmcnt(1)
	v_mfma_f32_16x16x32_bf16 v[36:39], v[40:43], v[132:135], v[96:99]
	v_mfma_f32_16x16x32_bf16 v[28:31], v[40:43], v[136:139], v[64:67]
	v_mfma_f32_16x16x32_bf16 v[16:19], v[40:43], v[140:143], v[16:19]
	v_mfma_f32_16x16x32_bf16 v[8:11], v[40:43], v[150:153], v[8:11]
	s_nop 0
	ds_read_b128 v[64:67], v144 offset:39936
	s_waitcnt lgkmcnt(1)
	v_mfma_f32_16x16x32_bf16 v[48:51], v[68:71], v[132:135], v[88:91]
	v_mfma_f32_16x16x32_bf16 v[40:43], v[68:71], v[136:139], v[56:59]
	v_mfma_f32_16x16x32_bf16 v[32:35], v[68:71], v[140:143], v[32:35]
	v_mfma_f32_16x16x32_bf16 v[20:23], v[68:71], v[150:153], v[20:23]
	s_waitcnt lgkmcnt(0)
	v_mfma_f32_16x16x32_bf16 v[56:59], v[64:67], v[132:135], v[76:79]
	v_mfma_f32_16x16x32_bf16 v[52:55], v[64:67], v[136:139], v[52:55]
	v_mfma_f32_16x16x32_bf16 v[44:47], v[64:67], v[140:143], v[44:47]
	v_mfma_f32_16x16x32_bf16 v[60:63], v[64:67], v[150:153], v[60:63]
	v_mov_b32_e32 v85, v147
	v_mov_b32_e32 v67, v147
	s_waitcnt vmcnt(0)
	s_barrier
	s_mov_b32 s4, 0xfffffc0
	v_and_b32_e32 v69, 15, v67
	v_lshrrev_b32_e32 v71, 1, v67
	v_and_b32_e32 v68, 64, v67
	v_and_or_b32 v69, v71, s4, v69
	s_movk_i32 s4, 0x210
	v_lshl_add_u32 v68, v68, 2, 0
	v_and_b32_e32 v67, 48, v67
	v_mul_lo_u32 v69, v69, s4
	v_lshlrev_b32_e32 v65, 3, v85
	v_lshlrev_b32_e32 v70, 2, v85
	v_add3_u32 v67, v68, v67, v69
	s_cmpk_lg_i32 s40, 0xb00
	v_and_b32_e32 v64, 31, v85
	v_and_b32_e32 v65, 0x80, v65
	v_and_b32_e32 v66, 60, v70
	ds_write_b128 v67, v[112:115] offset:192
	ds_write_b128 v67, v[108:111] offset:8448
	ds_write_b128 v67, v[100:103] offset:8512
	ds_write_b128 v67, v[92:95] offset:8576
	v_ashrrev_i32_e32 v103, 5, v85
	v_add_u32_e32 v71, 0x100, v85
	v_add_u32_e32 v87, 0x200, v85
	v_add_u32_e32 v89, 0x300, v85
	v_add_u32_e32 v90, 0x400, v85
	v_add_u32_e32 v91, 0x500, v85
	v_add_u32_e32 v92, 0x600, v85
	v_add_u32_e32 v93, 0x700, v85
	v_add_u32_e32 v94, 0x800, v85
	v_add_u32_e32 v108, 0x900, v85
	v_add_u32_e32 v109, 0xa00, v85
	v_add_u32_e32 v110, 0xb00, v85
	v_add_u32_e32 v111, 0xc00, v85
	v_add_u32_e32 v112, 0xd00, v85
	v_add_u32_e32 v113, 0xe00, v85
	v_add_u32_e32 v114, 0xf00, v85
	s_cselect_b64 s[42:43], -1, 0
	s_cmpk_eq_i32 s40, 0xb00
	v_lshl_add_u32 v64, v64, 4, 0
	ds_write_b128 v67, v[80:83] offset:16896
	s_mov_b64 s[44:45], -1
	v_add_u32_e32 v104, s38, v103
	v_lshlrev_b32_e32 v144, 1, v65
	v_lshlrev_b32_e32 v66, 1, v66
	v_ashrrev_i32_e32 v86, 5, v71
	v_ashrrev_i32_e32 v84, 5, v87
	v_ashrrev_i32_e32 v83, 5, v89
	v_ashrrev_i32_e32 v82, 5, v90
	v_ashrrev_i32_e32 v81, 5, v91
	v_ashrrev_i32_e32 v80, 5, v92
	v_ashrrev_i32_e32 v79, 5, v93
	v_ashrrev_i32_e32 v78, 5, v94
	v_ashrrev_i32_e32 v77, 5, v108
	v_ashrrev_i32_e32 v76, 5, v109
	v_ashrrev_i32_e32 v75, 5, v110
	v_ashrrev_i32_e32 v74, 5, v111
	v_ashrrev_i32_e32 v73, 5, v112
	v_ashrrev_i32_e32 v72, 5, v113
	v_ashrrev_i32_e32 v65, 5, v114
	ds_write_b128 v67, v[124:127]
	ds_write_b128 v67, v[120:123] offset:64
	ds_write_b128 v67, v[116:119] offset:128
	ds_write_b128 v67, v[170:173] offset:8640
	ds_write_b128 v67, v[158:161] offset:16960
	ds_write_b128 v67, v[162:165] offset:17024
	ds_write_b128 v67, v[174:177] offset:17088
	ds_write_b128 v67, v[128:131] offset:25344
	ds_write_b128 v67, v[154:157] offset:25408
	ds_write_b128 v67, v[166:169] offset:25472
	ds_write_b128 v67, v[178:181] offset:25536
	s_waitcnt lgkmcnt(0)
	s_barrier
; __device__ void phase_gemm_in(const Params& p, int l, unsigned char* smem) {
;     ...
;       if (!dv) {
; #pragma unroll
;         for (int i = 0; i < 16; ++i) {
;           int idx = tid + 256 * i, r = idx >> 5, c4 = idx & 31;
;           float4 x = *(const float4*)(ct + r * 132 + 4 * c4);
;           uint2 o2; o2.x = pack2(x.x, x.y); o2.y = pack2(x.z, x.w);
;           { typedef unsigned u2v __attribute__((ext_vector_type(2))); const u2v o_ = {o2.x, o2.y};
;             __builtin_nontemporal_store(o_, (u2v*)(p.Z + (size_t)(m0 + r) * DIN + n0 + (c4 >> 4) * 128 + hf * 64 + (c4 & 15) * 4)); }
;         }
	s_cbranch_scc1 .LBB0_404
	s_mul_i32 s48, s38, 0x1a00
	s_mul_hi_u32 s49, s38, 0x1a00
	s_add_u32 s48, s78, s48
	s_addc_u32 s49, s79, s49
	s_lshl_b32 s44, s40, 1
	v_lshrrev_b32_e32 v160, 4, v147
	v_and_b32_e32 v161, 15, v147
	v_mul_u32_u24_e32 v158, 0x1a00, v160
	v_mul_u32_u24_e32 v159, 0x210, v160
	v_and_b32_e32 v160, 8, v161
	v_lshl_add_u32 v159, v161, 5, v159
	v_and_b32_e32 v161, 7, v161
	v_lshlrev_b32_e32 v160, 5, v160
	v_lshl_or_b32 v160, v161, 4, v160
	v_add3_u32 v158, v158, v160, s44
	ds_read_b128 v[116:119], v159
	ds_read_b128 v[120:123], v159 offset:16
	ds_read_b128 v[124:127], v159 offset:8448
	ds_read_b128 v[128:131], v159 offset:8464
	s_waitcnt lgkmcnt(2)
	v_cvt_pk_bf16_f32 v164, v116, v117
	v_cvt_pk_bf16_f32 v165, v118, v119
	v_cvt_pk_bf16_f32 v166, v120, v121
	v_cvt_pk_bf16_f32 v167, v122, v123
	ds_read_b128 v[116:119], v159 offset:16896
	ds_read_b128 v[120:123], v159 offset:16912
	global_store_dwordx4 v158, v[164:167], s[48:49] offset:0 nt
	v_add_u32_e32 v158, 0x1a000, v158
	s_waitcnt lgkmcnt(2)
	v_cvt_pk_bf16_f32 v168, v124, v125
	v_cvt_pk_bf16_f32 v169, v126, v127
	v_cvt_pk_bf16_f32 v170, v128, v129
	v_cvt_pk_bf16_f32 v171, v130, v131
	ds_read_b128 v[124:127], v159 offset:25344
	ds_read_b128 v[128:131], v159 offset:25360
	global_store_dwordx4 v158, v[168:171], s[48:49] offset:0 nt
	v_add_u32_e32 v158, 0x1a000, v158
	s_waitcnt lgkmcnt(2)
	v_cvt_pk_bf16_f32 v164, v116, v117
	v_cvt_pk_bf16_f32 v165, v118, v119
	v_cvt_pk_bf16_f32 v166, v120, v121
	v_cvt_pk_bf16_f32 v167, v122, v123
	ds_read_b128 v[116:119], v159 offset:33792
	ds_read_b128 v[120:123], v159 offset:33808
	global_store_dwordx4 v158, v[164:167], s[48:49] offset:0 nt
	v_add_u32_e32 v158, 0x1a000, v158
	s_waitcnt lgkmcnt(2)
	v_cvt_pk_bf16_f32 v168, v124, v125
	v_cvt_pk_bf16_f32 v169, v126, v127
	v_cvt_pk_bf16_f32 v170, v128, v129
	v_cvt_pk_bf16_f32 v171, v130, v131
	ds_read_b128 v[124:127], v159 offset:42240
	ds_read_b128 v[128:131], v159 offset:42256
	global_store_dwordx4 v158, v[168:171], s[48:49] offset:0 nt
	v_add_u32_e32 v158, 0x1a000, v158
	s_waitcnt lgkmcnt(2)
	v_cvt_pk_bf16_f32 v164, v116, v117
	v_cvt_pk_bf16_f32 v165, v118, v119
	v_cvt_pk_bf16_f32 v166, v120, v121
	v_cvt_pk_bf16_f32 v167, v122, v123
	ds_read_b128 v[116:119], v159 offset:50688
	ds_read_b128 v[120:123], v159 offset:50704
	global_store_dwordx4 v158, v[164:167], s[48:49] offset:0 nt
	v_add_u32_e32 v158, 0x1a000, v158
	s_waitcnt lgkmcnt(2)
	v_cvt_pk_bf16_f32 v168, v124, v125
	v_cvt_pk_bf16_f32 v169, v126, v127
	v_cvt_pk_bf16_f32 v170, v128, v129
	v_cvt_pk_bf16_f32 v171, v130, v131
	ds_read_b128 v[124:127], v159 offset:59136
	ds_read_b128 v[128:131], v159 offset:59152
	global_store_dwordx4 v158, v[168:171], s[48:49] offset:0 nt
	v_add_u32_e32 v158, 0x1a000, v158
	s_waitcnt lgkmcnt(2)
	v_cvt_pk_bf16_f32 v164, v116, v117
	v_cvt_pk_bf16_f32 v165, v118, v119
	v_cvt_pk_bf16_f32 v166, v120, v121
	v_cvt_pk_bf16_f32 v167, v122, v123
	global_store_dwordx4 v158, v[164:167], s[48:49] offset:0 nt
	v_add_u32_e32 v158, 0x1a000, v158
	s_waitcnt lgkmcnt(0)
	v_cvt_pk_bf16_f32 v168, v124, v125
	v_cvt_pk_bf16_f32 v169, v126, v127
	v_cvt_pk_bf16_f32 v170, v128, v129
	v_cvt_pk_bf16_f32 v171, v130, v131
	global_store_dwordx4 v158, v[168:171], s[48:49] offset:0 nt
	s_mov_b64 s[44:45], 0

; __device__ void phase_gemm_in(const Params& p, int l, unsigned char* smem) {
;     ...
;     for (int hf = 0; hf < 2; ++hf) {
;       acc2_to_lds(acc, ct, hf);
;       if (!dv) {
; #pragma unroll
;         for (int i = 0; i < 16; ++i) {
;           int idx = tid + 256 * i, r = idx >> 5, c4 = idx & 31;
;           float4 x = *(const float4*)(ct + r * 132 + 4 * c4);
;           uint2 o2; o2.x = pack2(x.x, x.y); o2.y = pack2(x.z, x.w);
;           { typedef unsigned u2v __attribute__((ext_vector_type(2))); const u2v o_ = {o2.x, o2.y};
;             __builtin_nontemporal_store(o_, (u2v*)(p.Z + (size_t)(m0 + r) * DIN + n0 + (c4 >> 4) * 128 + hf * 64 + (c4 & 15) * 4)); }
;         }
.LBB0_406:
	v_mov_b32_e32 v67, v147
	s_barrier
	s_mov_b32 s4, 0xfffffc0
	v_and_b32_e32 v70, 15, v67
	v_lshrrev_b32_e32 v71, 1, v67
	v_and_b32_e32 v69, 64, v67
	v_and_or_b32 v70, v71, s4, v70
	v_lshl_add_u32 v69, v69, 2, 0
	v_and_b32_e32 v67, 48, v67
	v_mul_lo_u32 v70, v70, s5
	v_add3_u32 v67, v69, v67, v70
	s_andn2_b64 vcc, exec, s[42:43]
	s_mov_b64 s[42:43], -1
	ds_write_b128 v67, v[24:27]
	ds_write_b128 v67, v[36:39] offset:64
	ds_write_b128 v67, v[48:51] offset:128
	ds_write_b128 v67, v[56:59] offset:192
	ds_write_b128 v67, v[12:15] offset:8448
	ds_write_b128 v67, v[28:31] offset:8512
	ds_write_b128 v67, v[40:43] offset:8576
	ds_write_b128 v67, v[52:55] offset:8640
	ds_write_b128 v67, v[4:7] offset:16896
	ds_write_b128 v67, v[16:19] offset:16960
	ds_write_b128 v67, v[32:35] offset:17024
	ds_write_b128 v67, v[44:47] offset:17088
	ds_write_b128 v67, v[0:3] offset:25344
	ds_write_b128 v67, v[8:11] offset:25408
	ds_write_b128 v67, v[20:23] offset:25472
	ds_write_b128 v67, v[60:63] offset:25536
	s_waitcnt lgkmcnt(0)
	s_barrier
	s_cbranch_vccnz .LBB0_408
	s_mul_i32 s48, s38, 0x1a00
	s_mul_hi_u32 s49, s38, 0x1a00
	s_add_u32 s48, s78, s48
	s_addc_u32 s49, s79, s49
	s_lshl_b32 s44, s40, 1
	v_lshrrev_b32_e32 v26, 4, v147
	v_and_b32_e32 v27, 15, v147
	v_mul_u32_u24_e32 v24, 0x1a00, v26
	v_mul_u32_u24_e32 v25, 0x210, v26
	v_and_b32_e32 v26, 8, v27
	v_lshl_add_u32 v25, v27, 5, v25
	v_and_b32_e32 v27, 7, v27
	v_lshlrev_b32_e32 v26, 5, v26
	v_lshl_or_b32 v26, v27, 4, v26
	v_add3_u32 v24, v24, v26, s44
	ds_read_b128 v[0:3], v25
	ds_read_b128 v[4:7], v25 offset:16
	ds_read_b128 v[8:11], v25 offset:8448
	ds_read_b128 v[12:15], v25 offset:8464
	s_waitcnt lgkmcnt(2)
	v_cvt_pk_bf16_f32 v16, v0, v1
	v_cvt_pk_bf16_f32 v17, v2, v3
	v_cvt_pk_bf16_f32 v18, v4, v5
	v_cvt_pk_bf16_f32 v19, v6, v7
	ds_read_b128 v[0:3], v25 offset:16896
	ds_read_b128 v[4:7], v25 offset:16912
	global_store_dwordx4 v24, v[16:19], s[48:49] offset:128 nt
	v_add_u32_e32 v24, 0x1a000, v24
	s_waitcnt lgkmcnt(2)
	v_cvt_pk_bf16_f32 v20, v8, v9
	v_cvt_pk_bf16_f32 v21, v10, v11
	v_cvt_pk_bf16_f32 v22, v12, v13
	v_cvt_pk_bf16_f32 v23, v14, v15
	ds_read_b128 v[8:11], v25 offset:25344
	ds_read_b128 v[12:15], v25 offset:25360
	global_store_dwordx4 v24, v[20:23], s[48:49] offset:128 nt
	v_add_u32_e32 v24, 0x1a000, v24
	s_waitcnt lgkmcnt(2)
	v_cvt_pk_bf16_f32 v16, v0, v1
	v_cvt_pk_bf16_f32 v17, v2, v3
	v_cvt_pk_bf16_f32 v18, v4, v5
	v_cvt_pk_bf16_f32 v19, v6, v7
	ds_read_b128 v[0:3], v25 offset:33792
	ds_read_b128 v[4:7], v25 offset:33808
	global_store_dwordx4 v24, v[16:19], s[48:49] offset:128 nt
	v_add_u32_e32 v24, 0x1a000, v24
	s_waitcnt lgkmcnt(2)
	v_cvt_pk_bf16_f32 v20, v8, v9
	v_cvt_pk_bf16_f32 v21, v10, v11
	v_cvt_pk_bf16_f32 v22, v12, v13
	v_cvt_pk_bf16_f32 v23, v14, v15
	ds_read_b128 v[8:11], v25 offset:42240
	ds_read_b128 v[12:15], v25 offset:42256
	global_store_dwordx4 v24, v[20:23], s[48:49] offset:128 nt
	v_add_u32_e32 v24, 0x1a000, v24
	s_waitcnt lgkmcnt(2)
	v_cvt_pk_bf16_f32 v16, v0, v1
	v_cvt_pk_bf16_f32 v17, v2, v3
	v_cvt_pk_bf16_f32 v18, v4, v5
	v_cvt_pk_bf16_f32 v19, v6, v7
	ds_read_b128 v[0:3], v25 offset:50688
	ds_read_b128 v[4:7], v25 offset:50704
	global_store_dwordx4 v24, v[16:19], s[48:49] offset:128 nt
	v_add_u32_e32 v24, 0x1a000, v24
	s_waitcnt lgkmcnt(2)
	v_cvt_pk_bf16_f32 v20, v8, v9
	v_cvt_pk_bf16_f32 v21, v10, v11
	v_cvt_pk_bf16_f32 v22, v12, v13
	v_cvt_pk_bf16_f32 v23, v14, v15
	ds_read_b128 v[8:11], v25 offset:59136
	ds_read_b128 v[12:15], v25 offset:59152
	global_store_dwordx4 v24, v[20:23], s[48:49] offset:128 nt
	v_add_u32_e32 v24, 0x1a000, v24
	s_waitcnt lgkmcnt(2)
	v_cvt_pk_bf16_f32 v16, v0, v1
	v_cvt_pk_bf16_f32 v17, v2, v3
	v_cvt_pk_bf16_f32 v18, v4, v5
	v_cvt_pk_bf16_f32 v19, v6, v7
	global_store_dwordx4 v24, v[16:19], s[48:49] offset:128 nt
	v_add_u32_e32 v24, 0x1a000, v24
	s_waitcnt lgkmcnt(0)
	v_cvt_pk_bf16_f32 v20, v8, v9
	v_cvt_pk_bf16_f32 v21, v10, v11
	v_cvt_pk_bf16_f32 v22, v12, v13
	v_cvt_pk_bf16_f32 v23, v14, v15
	global_store_dwordx4 v24, v[20:23], s[48:49] offset:128 nt
	s_mov_b64 s[42:43], 0
